# modulate phase: MODF items of batch x computed by class x, so the seam after modulate is XCD-local too
# speedup vs baseline: 1.0311x; 1.0083x over previous
; DI void phase_modulate(const float* xin, const float* norm_w, const float* modp, const float* adab,
;                        bf16* H, LAS unsigned char* lds, int tid, int G, float* MODF, const float* MODP_all, const float* adab_all) {
;     ...
;     if (MODF) for (int idx = blockIdx.x * 512 + tid; idx < 2 * 8 * 3072; idx += G * 512) { const int l2 = idx / 24576, rem = idx - l2 * 24576, b2 = rem / 3072, c2 = rem - b2 * 3072;
;         float v = adab_all[l2 * 3072 + c2];
; #pragma unroll
;         for (int ks = 0; ks < 8; ++ks) v += MODP_all[((size_t)(l2 * 8 + ks) * 8 + b2) * 3072 + c2];
;         MODF[idx] = v; }
.LBB0_93:
	s_mul_i32 s2, s18, 6
	s_and_b64 s[4:5], s[94:95], exec
	v_writelane_b32 v255, s2, 26
	s_mov_b32 s19, s35
	v_readlane_b32 s36, v253, 26
	v_readlane_b32 s4, v253, 50
	v_writelane_b32 v255, s18, 27
	v_readlane_b32 s37, v253, 27
	v_readlane_b32 s5, v253, 51
	v_writelane_b32 v255, s19, 28
	s_cselect_b32 s19, s37, s79
	s_cselect_b32 s18, s36, s78
	s_and_b64 s[0:1], s[4:5], s[0:1]
	v_writelane_b32 v255, s0, 29
	s_mov_b64 s[20:21], -1
	v_readlane_b32 s38, v253, 28
	v_writelane_b32 v255, s1, 30
	s_xor_b64 s[0:1], s[0:1], -1
	v_writelane_b32 v255, s0, 31
	s_and_b64 vcc, exec, s[0:1]
	v_readlane_b32 s39, v253, 29
	v_writelane_b32 v255, s1, 32
	v_readlane_b32 s40, v253, 30
	v_readlane_b32 s41, v253, 31
	v_readlane_b32 s42, v253, 32
	v_readlane_b32 s43, v253, 33
	v_readlane_b32 s44, v253, 34
	v_readlane_b32 s45, v253, 35
	v_readlane_b32 s46, v253, 36
	v_readlane_b32 s47, v253, 37
	v_readlane_b32 s48, v253, 38
	v_readlane_b32 s49, v253, 39
	v_readlane_b32 s50, v253, 40
	v_readlane_b32 s51, v253, 41
	s_cbranch_vccz .LBB0_159
	v_readlane_b32 s0, v255, 26
	s_or_b32 s2, s0, 1
	s_cmp_le_i32 s82, s2
	s_cselect_b64 s[20:21], -1, 0
	s_cmp_gt_i32 s82, s2
	s_cselect_b64 s[0:1], -1, 0
	s_cmp_ge_i32 s2, s83
	s_cselect_b64 s[4:5], -1, 0
	s_or_b64 s[0:1], s[0:1], s[4:5]
	s_and_b64 vcc, exec, s[0:1]
	s_cbranch_vccnz .LBB0_112
	v_readlane_b32 s0, v253, 0
	v_mbcnt_lo_u32_b32 v20, -1, 0
	v_mbcnt_hi_u32_b32 v20, -1, v20
	s_lshr_b32 s2, s66, 3
	s_lshl_b32 s2, s2, 9
	v_add_u32_e32 v76, s0, v20
	v_readlane_b32 s0, v253, 54
	v_readlane_b32 s1, v253, 55
	v_add_u32_e32 v4, s2, v76
	v_mov_b32_e32 v6, v4
	s_movk_i32 s2, 0xbff
	v_cmp_lt_i32_e32 vcc, s2, v4
	v_add_u32_e32 v5, 0x5400, v4
	s_nop 1
	v_cndmask_b32_e32 v4, v4, v5, vcc
	s_and_b32 s2, s66, 7
	s_mul_i32 s2, s2, 0xc00
	v_add_u32_e32 v4, s2, v4
	s_movk_i32 s2, 0x1800
	s_and_b64 s[0:1], s[94:95], s[0:1]
	v_cmp_gt_i32_e32 vcc, s2, v6
	s_and_b64 s[4:5], s[0:1], vcc
	s_and_saveexec_b64 s[0:1], s[4:5]
	v_readlane_b32 s36, v253, 26
	v_readlane_b32 s44, v253, 34
	v_readlane_b32 s45, v253, 35
	s_movk_i32 s16, 0xa000
	v_readlane_b32 s37, v253, 27
	v_readlane_b32 s38, v253, 28
	v_readlane_b32 s39, v253, 29
	v_readlane_b32 s40, v253, 30
	v_readlane_b32 s41, v253, 31
	v_readlane_b32 s42, v253, 32
	v_readlane_b32 s43, v253, 33
	v_readlane_b32 s46, v253, 36
	v_readlane_b32 s47, v253, 37
	v_readlane_b32 s48, v253, 38
	v_readlane_b32 s49, v253, 39
	v_readlane_b32 s50, v253, 40
	v_readlane_b32 s51, v253, 41
	s_cbranch_execz .LBB0_98
	v_readlane_b32 s4, v253, 48
	s_waitcnt lgkmcnt(0)
	v_ashrrev_i32_e32 v5, 31, v4
	v_readlane_b32 s5, v253, 49
	s_mov_b64 s[26:27], 0
	s_nop 0
	v_lshl_add_u64 v[6:7], v[4:5], 2, s[4:5]

; __device__ __forceinline__ unsigned xb_ld(unsigned* p)              { return __hip_atomic_load(p, __ATOMIC_RELAXED, __HIP_MEMORY_SCOPE_AGENT); }
; __device__ __forceinline__ unsigned xb_add(unsigned* p, unsigned v) { return __hip_atomic_fetch_add(p, v, __ATOMIC_RELAXED, __HIP_MEMORY_SCOPE_AGENT); }
; #define XB_SPIN(cond, bar) do { unsigned _sp = 0; while (cond) { __builtin_amdgcn_s_sleep(1); \
;     if ((++_sp & 255u) == 0u) { if (xb_ld(&(bar)[XB_TMO])) break; if (_sp > XB_SPIN_CAP) { atomicAdd(&(bar)[XB_TMO], 1u); break; } } } } while (0)
; __device__ __forceinline__ void xcd_barrier(const XcdBarrier& b) {
;     asm volatile("s_waitcnt vmcnt(0)" ::: "memory");
;     __syncthreads();
;     if (threadIdx.x == 0) {
;         unsigned* bar = b.bar;
;         __builtin_amdgcn_s_waitcnt(0);
;         unsigned nloc = b.st[0], nx = b.st[1];
;         if (nloc == 0u) { xcd_barrier_complete(bar, b.x, nloc, nx); b.st[0] = nloc; b.st[1] = nx; }
;         const unsigned old = xb_add(&bar[XB_XSUB(b.x)], 1u);
;         const unsigned gen = old / nloc;
;         if (old + 1u == (gen + 1u) * nloc) {
;             __builtin_amdgcn_fence(__ATOMIC_RELEASE, "agent");
;             asm volatile("s_waitcnt vmcnt(0)" ::: "memory");
;             const unsigned og = xb_add(&bar[XB_TOP], 1u);
;             const unsigned tg = og / nx;
;             if (og + 1u == (tg + 1u) * nx) xb_add(&bar[XB_TOPGEN], 1u);
;             else XB_SPIN(xb_ld(&bar[XB_TOPGEN]) == tg, bar);
;             __builtin_amdgcn_fence(__ATOMIC_ACQUIRE, "agent");
;             xb_add(&bar[XB_XGEN(b.x)], 1u);
;             asm volatile("s_waitcnt vmcnt(0)" ::: "memory");
;         } else {
;             XB_SPIN(xb_ld(&bar[XB_XGEN(b.x)]) == gen, bar);
;             __builtin_amdgcn_fence(__ATOMIC_ACQUIRE, "agent");
;             asm volatile("s_waitcnt vmcnt(0)" ::: "memory");
;         }
;     }
;     __syncthreads();
; }
.LBB0_112:
	v_readlane_b32 s0, v255, 26
	s_add_i32 s2, s0, 2
	s_cmp_lt_i32 s2, s83
	s_cselect_b64 s[0:1], -1, 0
	s_and_b64 s[0:1], s[20:21], s[0:1]
	s_andn2_b64 vcc, exec, s[0:1]
	s_cbranch_vccnz .LBB0_158
	v_readlane_b32 s20, v253, 1
	v_readlane_b32 s21, v253, 2
	s_waitcnt vmcnt(0)
	s_barrier
	v_readlane_b32 s98, v255, 41
	s_cmp_lg_u32 s98, 0
	s_cbranch_scc0 .Lfs6_slow
	v_readlane_b32 s98, v253, 0
	s_cmp_lg_u32 s98, 0
	s_cbranch_scc1 .Lfs6_join
	v_readlane_b32 vcc_lo, v255, 42
	s_and_b32 s98, s66, 7
	s_lshl_b32 s98, s98, 7
	s_add_u32 s98, s98, 0x1783a00
	s_add_u32 s98, s80, s98
	s_addc_u32 s99, s81, 0
	s_add_i32 vcc_lo, vcc_lo, 1
	s_lshr_b32 vcc_hi, s66, 3
	s_lshl_b32 vcc_hi, vcc_hi, 2
	v_writelane_b32 v255, vcc_lo, 42
	v_mbcnt_lo_u32_b32 v5, -1, 0
	v_lshlrev_b32_e32 v5, 2, v5
	v_mov_b32_e32 v6, vcc_lo
	v_mov_b32_e32 v7, vcc_hi
	s_mov_b32 m0, 0
	s_mov_b64 exec, 1
	global_store_dword v7, v6, s[98:99]
	buffer_inv sc1
	s_mov_b32 exec_lo, -1
	s_mov_b32 exec_hi, 0

; __device__ __forceinline__ unsigned xb_ld(unsigned* p)              { return __hip_atomic_load(p, __ATOMIC_RELAXED, __HIP_MEMORY_SCOPE_AGENT); }
; __device__ __forceinline__ unsigned xb_add(unsigned* p, unsigned v) { return __hip_atomic_fetch_add(p, v, __ATOMIC_RELAXED, __HIP_MEMORY_SCOPE_AGENT); }
; #define XB_SPIN(cond, bar) do { unsigned _sp = 0; while (cond) { __builtin_amdgcn_s_sleep(1); \
;     if ((++_sp & 255u) == 0u) { if (xb_ld(&(bar)[XB_TMO])) break; if (_sp > XB_SPIN_CAP) { atomicAdd(&(bar)[XB_TMO], 1u); break; } } } } while (0)
; __device__ __forceinline__ void xcd_barrier(const XcdBarrier& b) {
;     asm volatile("s_waitcnt vmcnt(0)" ::: "memory");
;     __syncthreads();
;     if (threadIdx.x == 0) {
;         unsigned* bar = b.bar;
;         __builtin_amdgcn_s_waitcnt(0);
;         unsigned nloc = b.st[0], nx = b.st[1];
;         if (nloc == 0u) { xcd_barrier_complete(bar, b.x, nloc, nx); b.st[0] = nloc; b.st[1] = nx; }
;         const unsigned old = xb_add(&bar[XB_XSUB(b.x)], 1u);
;         const unsigned gen = old / nloc;
;         if (old + 1u == (gen + 1u) * nloc) {
;             __builtin_amdgcn_fence(__ATOMIC_RELEASE, "agent");
;             asm volatile("s_waitcnt vmcnt(0)" ::: "memory");
;             const unsigned og = xb_add(&bar[XB_TOP], 1u);
;             const unsigned tg = og / nx;
;             if (og + 1u == (tg + 1u) * nx) xb_add(&bar[XB_TOPGEN], 1u);
;             else XB_SPIN(xb_ld(&bar[XB_TOPGEN]) == tg, bar);
;             __builtin_amdgcn_fence(__ATOMIC_ACQUIRE, "agent");
;             xb_add(&bar[XB_XGEN(b.x)], 1u);
;             asm volatile("s_waitcnt vmcnt(0)" ::: "memory");
;         } else {
;             XB_SPIN(xb_ld(&bar[XB_XGEN(b.x)]) == gen, bar);
;             __builtin_amdgcn_fence(__ATOMIC_ACQUIRE, "agent");
;             asm volatile("s_waitcnt vmcnt(0)" ::: "memory");
;         }
;     }
;     __syncthreads();
; }
.Lfs6_slow:
	s_mov_b64 s[0:1], exec
	v_readlane_b32 s4, v253, 3
	v_readlane_b32 s5, v253, 4
	s_and_b64 s[4:5], s[0:1], s[4:5]
	s_mov_b64 exec, s[4:5]
	s_cbranch_execz .LBB0_157
	v_readlane_b32 s4, v255, 11
	s_waitcnt vmcnt(0) expcnt(0) lgkmcnt(0)
	s_nop 0
	v_mov_b32_e32 v4, s4
	ds_read_b32 v6, v4
	v_readlane_b32 s4, v255, 12
	s_waitcnt lgkmcnt(0)
	v_cmp_ne_u32_e32 vcc, 0, v6
	v_mov_b32_e32 v4, s4
	ds_read_b32 v4, v4
	s_cbranch_vccnz .LBB0_128
	s_add_u32 s26, s20, 0x1000
	s_addc_u32 s27, s21, 0
	s_add_u32 s30, s20, 0x1100
	s_addc_u32 s31, s21, 0
	s_add_u32 s36, s20, 0x1200
	s_addc_u32 s37, s21, 0
	s_add_u32 s38, s20, 0x1300
	s_addc_u32 s39, s21, 0
	s_mov_b32 s4, 1
	s_mov_b64 s[40:41], 0
	s_branch .LBB0_118
